# v27 + P2 token loop: 44 lane-xor ds_bpermute (butterfly reductions, rotary partner exchange) replaced by exact DPP moves (quad_perm / row_shl+shr:4 / row_ror:8)
# speedup vs baseline: 1.0117x; 1.0060x over previous
.LBB0_646:
	v_lshl_add_u64 v[66:67], s[24:25], 0, v[124:125]
	global_load_dwordx2 v[154:155], v[66:67], off
	global_load_dwordx4 v[70:73], v[76:77], off
	global_load_dwordx2 v[68:69], v[66:67], off offset:512
	global_load_dwordx2 v[156:157], v[66:67], off offset:2560
	global_load_dwordx2 v[152:153], v[66:67], off offset:3072
	s_movk_i32 s0, 0x1000
	v_add_co_u32_e32 v142, vcc, s0, v66
	v_add_u32_e32 v173, 8, v173
	s_nop 0
	v_addc_co_u32_e32 v143, vcc, 0, v67, vcc
	global_load_dwordx2 v[150:151], v[66:67], off offset:3584
	global_load_dwordx2 v[146:147], v[142:143], off
	s_waitcnt lgkmcnt(0)
	global_load_dwordx2 v[148:149], v[142:143], off offset:512
	global_load_dwordx2 v[144:145], v[142:143], off offset:1024
	s_nop 0
	global_load_dwordx2 v[142:143], v[142:143], off offset:1536
	v_add_u32_e32 v180, s59, v173
	s_andn2_b64 vcc, exec, s[12:13]
	s_waitcnt vmcnt(0)
	v_lshlrev_b32_e32 v66, 16, v154
	v_and_b32_e32 v67, 0xffff0000, v154
	v_lshlrev_b32_e32 v154, 16, v155
	v_and_b32_e32 v155, 0xffff0000, v155
	v_pk_mul_f32 v[176:177], v[66:67], v[66:67]
	v_pk_mul_f32 v[178:179], v[154:155], v[154:155]
	v_add_f32_e32 v176, v176, v177
	v_add_f32_e32 v176, v178, v176
	v_add_f32_e32 v176, v179, v176
	s_nop 1
	v_mov_b32_dpp v177, v176 quad_perm:[1,0,3,2] row_mask:0xf bank_mask:0xf
	v_cndmask_b32_e64 v179, 0, 1, s[12:13]
	v_cmp_ne_u32_e64 s[72:73], 1, v179
	s_waitcnt lgkmcnt(0)
	v_add_f32_e32 v176, v176, v177
	s_nop 1
	v_mov_b32_dpp v177, v176 quad_perm:[2,3,0,1] row_mask:0xf bank_mask:0xf
	s_waitcnt lgkmcnt(0)
	v_add_f32_e32 v176, v176, v177
	s_nop 1
	v_mov_b32_dpp v177, v176 row_shl:4 row_mask:0xf bank_mask:0x5
	v_mov_b32_dpp v177, v176 row_shr:4 row_mask:0xf bank_mask:0xa
	s_waitcnt lgkmcnt(0)
	v_add_f32_e32 v177, v176, v177
	s_nop 1
	v_mov_b32_dpp v178, v177 row_ror:8 row_mask:0xf bank_mask:0xf
	v_and_b32_e32 v176, 63, v173
	s_waitcnt lgkmcnt(0)
	v_add_f32_e32 v177, v177, v178
	v_fmamk_f32 v177, v177, 0x3c800000, v219
	v_mul_f32_e32 v178, 0x4b800000, v177
	v_cmp_gt_f32_e64 s[0:1], s33, v177
	s_nop 1
	v_cndmask_b32_e64 v177, v177, v178, s[0:1]
	v_rsq_f32_e32 v178, v177
	v_ashrrev_i32_e32 v177, 6, v180
	v_mul_f32_e32 v179, 0x45800000, v178
	v_cndmask_b32_e64 v178, v178, v179, s[0:1]
	v_pk_mul_f32 v[70:71], v[70:71], v[178:179] op_sel_hi:[1,0]
	v_pk_mul_f32 v[72:73], v[72:73], v[178:179] op_sel_hi:[1,0]
	v_pk_mul_f32 v[70:71], v[70:71], v[66:67]
	v_pk_mul_f32 v[66:67], v[72:73], v[154:155]
	v_cndmask_b32_e64 v178, v176, v177, s[40:41]
	s_cbranch_vccnz .LBB0_648
	v_lshl_or_b32 v154, v178, 5, v159
	v_readlane_b32 s0, v250, 10
	v_ashrrev_i32_e32 v155, 31, v154
	v_readlane_b32 s1, v250, 11
	v_mov_b32_dpp v72, v70 row_shl:4 row_mask:0xf bank_mask:0x5
	v_mov_b32_dpp v72, v70 row_shr:4 row_mask:0xf bank_mask:0xa
	v_mov_b32_dpp v73, v71 row_shl:4 row_mask:0xf bank_mask:0x5
	v_mov_b32_dpp v73, v71 row_shr:4 row_mask:0xf bank_mask:0xa
	v_lshl_add_u64 v[154:155], v[154:155], 2, s[0:1]
	global_load_dwordx4 v[180:183], v[154:155], off offset:16
	global_load_dwordx4 v[184:187], v[154:155], off
	s_waitcnt vmcnt(0)
	v_mov_b32_e32 v155, v186
	v_mov_b32_e32 v186, v185
	s_waitcnt lgkmcnt(0)
	v_pk_mul_f32 v[72:73], v[186:187], v[72:73]
	v_mov_b32_e32 v154, v184
	v_cndmask_b32_e64 v73, v73, -v73, s[42:43]
	v_cndmask_b32_e64 v72, v72, -v72, s[42:43]
	v_pk_fma_f32 v[70:71], v[70:71], v[154:155], v[72:73]
	v_mov_b32_dpp v72, v66 row_shl:4 row_mask:0xf bank_mask:0x5
	v_mov_b32_dpp v72, v66 row_shr:4 row_mask:0xf bank_mask:0xa
	v_mov_b32_dpp v73, v67 row_shl:4 row_mask:0xf bank_mask:0x5
	v_mov_b32_dpp v73, v67 row_shr:4 row_mask:0xf bank_mask:0xa
	v_mov_b32_e32 v155, v182
	v_mov_b32_e32 v182, v181
	v_mov_b32_e32 v154, v180
	s_waitcnt lgkmcnt(0)
	v_pk_mul_f32 v[72:73], v[182:183], v[72:73]
	s_nop 0
	v_cndmask_b32_e64 v73, v73, -v73, s[42:43]
	v_cndmask_b32_e64 v72, v72, -v72, s[42:43]
	v_pk_fma_f32 v[66:67], v[66:67], v[154:155], v[72:73]
.LBB0_648:
	s_mov_b32 s0, 0x3e38aa3b
	v_pk_mul_f32 v[70:71], v[70:71], s[0:1] op_sel_hi:[1,0]
	v_pk_mul_f32 v[66:67], v[66:67], s[0:1] op_sel_hi:[1,0]
	v_lshl_add_u64 v[154:155], s[24:25], 0, v[130:131]
	v_cvt_pk_bf16_f32 v70, v70, v71
	v_cvt_pk_bf16_f32 v71, v66, v67
	v_add_co_u32_e32 v66, vcc, 0x13000000, v154
	s_nop 1
	v_addc_co_u32_e32 v67, vcc, 0, v155, vcc
	global_store_dwordx2 v[66:67], v[70:71], off
	global_load_dwordx4 v[70:73], v[78:79], off
	v_lshlrev_b32_e32 v66, 16, v68
	v_and_b32_e32 v67, 0xffff0000, v68
	v_pk_mul_f32 v[180:181], v[66:67], v[66:67]
	v_lshlrev_b32_e32 v68, 16, v69
	v_and_b32_e32 v69, 0xffff0000, v69
	v_pk_mul_f32 v[182:183], v[68:69], v[68:69]
	v_add_f32_e32 v179, v180, v181
	v_add_f32_e32 v179, v182, v179
	v_add_f32_e32 v179, v183, v179
	s_nop 1
	v_mov_b32_dpp v180, v179 quad_perm:[1,0,3,2] row_mask:0xf bank_mask:0xf
	s_waitcnt lgkmcnt(0)
	v_add_f32_e32 v179, v179, v180
	s_nop 1
	v_mov_b32_dpp v180, v179 quad_perm:[2,3,0,1] row_mask:0xf bank_mask:0xf
	s_waitcnt lgkmcnt(0)
	v_add_f32_e32 v179, v179, v180
	s_nop 1
	v_mov_b32_dpp v180, v179 row_shl:4 row_mask:0xf bank_mask:0x5
	v_mov_b32_dpp v180, v179 row_shr:4 row_mask:0xf bank_mask:0xa
	s_waitcnt lgkmcnt(0)
	v_add_f32_e32 v179, v179, v180
	s_nop 1
	v_mov_b32_dpp v180, v179 row_ror:8 row_mask:0xf bank_mask:0xf
	s_waitcnt lgkmcnt(0)
	v_add_f32_e32 v179, v179, v180
	v_fmamk_f32 v179, v179, 0x3c800000, v219
	v_cmp_gt_f32_e32 vcc, s33, v179
	v_mul_f32_e32 v180, 0x4b800000, v179
	s_nop 0
	v_cndmask_b32_e32 v179, v179, v180, vcc
	v_rsq_f32_e32 v179, v179
	s_nop 0
	v_mul_f32_e32 v180, 0x45800000, v179
	v_cndmask_b32_e32 v180, v179, v180, vcc
	v_pk_mul_f32 v[182:183], v[180:181], v[66:67] op_sel_hi:[0,1]
	v_pk_mul_f32 v[180:181], v[180:181], v[68:69] op_sel_hi:[0,1]
	s_and_b64 vcc, exec, s[72:73]
	s_waitcnt vmcnt(0)
	v_pk_mul_f32 v[70:71], v[70:71], v[182:183]
	v_pk_mul_f32 v[72:73], v[72:73], v[180:181]
	s_cbranch_vccnz .LBB0_650
	v_lshl_or_b32 v178, v178, 5, v159
	v_readlane_b32 s0, v250, 10
	v_ashrrev_i32_e32 v179, 31, v178
	v_readlane_b32 s1, v250, 11
	v_mov_b32_dpp v186, v70 row_shl:4 row_mask:0xf bank_mask:0x5
	v_mov_b32_dpp v186, v70 row_shr:4 row_mask:0xf bank_mask:0xa
	v_mov_b32_dpp v187, v71 row_shl:4 row_mask:0xf bank_mask:0x5
	v_mov_b32_dpp v187, v71 row_shr:4 row_mask:0xf bank_mask:0xa
	v_lshl_add_u64 v[182:183], v[178:179], 2, s[0:1]
	global_load_dwordx4 v[178:181], v[182:183], off offset:16
	s_nop 0
	global_load_dwordx4 v[182:185], v[182:183], off
	s_waitcnt vmcnt(0)
	v_mov_b32_e32 v189, v184
	v_mov_b32_e32 v184, v183
	v_mov_b32_e32 v188, v182
	s_waitcnt lgkmcnt(0)
	v_pk_mul_f32 v[182:183], v[184:185], v[186:187]
	v_mov_b32_e32 v185, v180
	v_cndmask_b32_e64 v183, v183, -v183, s[42:43]
	v_cndmask_b32_e64 v182, v182, -v182, s[42:43]
	v_pk_fma_f32 v[70:71], v[70:71], v[188:189], v[182:183]
	v_mov_b32_dpp v182, v72 row_shl:4 row_mask:0xf bank_mask:0x5
	v_mov_b32_dpp v182, v72 row_shr:4 row_mask:0xf bank_mask:0xa
	v_mov_b32_dpp v183, v73 row_shl:4 row_mask:0xf bank_mask:0x5
	v_mov_b32_dpp v183, v73 row_shr:4 row_mask:0xf bank_mask:0xa
	v_mov_b32_e32 v180, v179
	v_mov_b32_e32 v184, v178
	s_waitcnt lgkmcnt(0)
	v_pk_mul_f32 v[178:179], v[180:181], v[182:183]
	s_nop 0
	v_cndmask_b32_e64 v179, v179, -v179, s[42:43]
	v_cndmask_b32_e64 v178, v178, -v178, s[42:43]
	v_pk_fma_f32 v[72:73], v[72:73], v[184:185], v[178:179]

.LBB0_656:
	s_or_b64 exec, exec, s[8:9]
	v_lshlrev_b32_e32 v66, 16, v156
	v_and_b32_e32 v67, 0xffff0000, v156
	v_lshlrev_b32_e32 v68, 16, v157
	v_and_b32_e32 v69, 0xffff0000, v157
	s_and_b64 vcc, exec, s[72:73]
	v_cndmask_b32_e64 v156, v176, v177, s[42:43]
	s_cbranch_vccnz .LBB0_658
	v_lshl_or_b32 v70, v156, 4, v160
	v_readlane_b32 s8, v251, 13
	v_ashrrev_i32_e32 v71, 31, v70
	v_readlane_b32 s9, v251, 14
	v_mov_b32_dpp v180, v66 quad_perm:[2,3,0,1] row_mask:0xf bank_mask:0xf
	v_mov_b32_dpp v181, v67 quad_perm:[2,3,0,1] row_mask:0xf bank_mask:0xf
	v_lshl_add_u64 v[176:177], v[70:71], 2, s[8:9]
	global_load_dwordx4 v[70:73], v[176:177], off offset:16
	s_nop 0
	global_load_dwordx4 v[176:179], v[176:177], off
	s_waitcnt vmcnt(0)
	v_mov_b32_e32 v183, v178
	v_mov_b32_e32 v178, v177
	v_mov_b32_e32 v182, v176
	s_waitcnt lgkmcnt(0)
	v_pk_mul_f32 v[176:177], v[178:179], v[180:181]
	v_mov_b32_e32 v179, v72
	v_cndmask_b32_e64 v177, v177, -v177, s[46:47]
	v_cndmask_b32_e64 v176, v176, -v176, s[46:47]
	v_pk_fma_f32 v[66:67], v[182:183], v[66:67], v[176:177]
	v_mov_b32_dpp v176, v68 quad_perm:[2,3,0,1] row_mask:0xf bank_mask:0xf
	v_mov_b32_dpp v177, v69 quad_perm:[2,3,0,1] row_mask:0xf bank_mask:0xf
	v_mov_b32_e32 v72, v71
	v_mov_b32_e32 v178, v70
	s_waitcnt lgkmcnt(0)
	v_pk_mul_f32 v[70:71], v[72:73], v[176:177]
	s_nop 0
	v_cndmask_b32_e64 v71, v71, -v71, s[46:47]
	v_cndmask_b32_e64 v70, v70, -v70, s[46:47]
	v_pk_fma_f32 v[68:69], v[178:179], v[68:69], v[70:71]
.LBB0_658:
	s_mov_b32 s8, 0x3e8293ee
	v_pk_mul_f32 v[66:67], v[66:67], s[8:9] op_sel_hi:[1,0]
	v_pk_mul_f32 v[68:69], v[68:69], s[8:9] op_sel_hi:[1,0]
	s_brev_b32 s8, 40
	v_cvt_pk_bf16_f32 v66, v66, v67
	v_cvt_pk_bf16_f32 v67, v68, v69
	v_add_co_u32_e32 v68, vcc, s8, v154
	s_nop 1
	v_addc_co_u32_e32 v69, vcc, 0, v155, vcc
	global_store_dwordx2 v[68:69], v[66:67], off
	v_lshlrev_b32_e32 v66, 16, v152
	v_and_b32_e32 v67, 0xffff0000, v152
	v_lshlrev_b32_e32 v68, 16, v153
	s_and_b64 vcc, exec, s[72:73]
	v_and_b32_e32 v69, 0xffff0000, v153
	s_cbranch_vccnz .LBB0_660
	v_lshl_or_b32 v70, v156, 4, v160
	v_readlane_b32 s8, v251, 13
	v_ashrrev_i32_e32 v71, 31, v70
	v_readlane_b32 s9, v251, 14
	v_mov_b32_dpp v152, v66 quad_perm:[2,3,0,1] row_mask:0xf bank_mask:0xf
	v_mov_b32_dpp v153, v67 quad_perm:[2,3,0,1] row_mask:0xf bank_mask:0xf
	v_lshl_add_u64 v[176:177], v[70:71], 2, s[8:9]
	global_load_dwordx4 v[70:73], v[176:177], off offset:16
	s_nop 0
	global_load_dwordx4 v[176:179], v[176:177], off
	s_waitcnt vmcnt(0)
	v_mov_b32_e32 v181, v178
	v_mov_b32_e32 v178, v177
	s_waitcnt lgkmcnt(0)
	v_pk_mul_f32 v[152:153], v[178:179], v[152:153]
	v_mov_b32_e32 v180, v176
	v_cndmask_b32_e64 v153, v153, -v153, s[46:47]
	v_cndmask_b32_e64 v152, v152, -v152, s[46:47]
	v_pk_fma_f32 v[66:67], v[180:181], v[66:67], v[152:153]
	v_mov_b32_dpp v152, v68 quad_perm:[2,3,0,1] row_mask:0xf bank_mask:0xf
	v_mov_b32_dpp v153, v69 quad_perm:[2,3,0,1] row_mask:0xf bank_mask:0xf
	v_mov_b32_e32 v177, v72
	v_mov_b32_e32 v72, v71
	v_mov_b32_e32 v176, v70
	s_waitcnt lgkmcnt(0)
	v_pk_mul_f32 v[70:71], v[72:73], v[152:153]
	s_nop 0
	v_cndmask_b32_e64 v71, v71, -v71, s[46:47]
	v_cndmask_b32_e64 v70, v70, -v70, s[46:47]
	v_pk_fma_f32 v[68:69], v[176:177], v[68:69], v[70:71]

.LBB0_664:
	v_lshlrev_b32_e32 v72, 16, v146
	v_and_b32_e32 v73, 0xffff0000, v146
	v_lshlrev_b32_e32 v66, 16, v148
	v_and_b32_e32 v67, 0xffff0000, v148
	v_lshlrev_b32_e32 v68, 16, v149
	v_and_b32_e32 v69, 0xffff0000, v149
	v_pk_mul_f32 v[148:149], v[72:73], v[72:73]
	v_and_b32_e32 v70, 0xffff0000, v147
	v_lshlrev_b32_e32 v71, 16, v147
	v_pk_mul_f32 v[146:147], v[70:71], v[70:71]
	v_add_f32_e32 v148, v148, v149
	v_add_f32_e32 v147, v147, v148
	v_add_f32_e32 v150, v146, v147
	v_pk_mul_f32 v[146:147], v[66:67], v[66:67]
	v_pk_mul_f32 v[148:149], v[68:69], v[68:69]
	v_add_f32_e32 v146, v146, v147
	v_add_f32_e32 v146, v148, v146
	v_add_f32_e32 v146, v149, v146
	v_cndmask_b32_e64 v149, 0, v150, s[54:55]
	v_cndmask_b32_e64 v146, 0, v146, s[50:51]
	v_cndmask_b32_e64 v147, 0, v150, s[48:49]
	v_add_f32_e32 v146, v149, v146
	s_nop 1
	v_mov_b32_dpp v148, v147 quad_perm:[1,0,3,2] row_mask:0xf bank_mask:0xf
	v_mov_b32_dpp v149, v146 quad_perm:[1,0,3,2] row_mask:0xf bank_mask:0xf
	s_waitcnt lgkmcnt(0)
	v_add_f32_e32 v147, v147, v148
	s_waitcnt lgkmcnt(0)
	v_add_f32_e32 v146, v146, v149
	v_mov_b32_dpp v148, v147 quad_perm:[2,3,0,1] row_mask:0xf bank_mask:0xf
	s_nop 1
	v_mov_b32_dpp v149, v146 quad_perm:[2,3,0,1] row_mask:0xf bank_mask:0xf
	s_waitcnt lgkmcnt(0)
	v_add_f32_e32 v147, v147, v148
	s_waitcnt lgkmcnt(0)
	v_add_f32_e32 v146, v146, v149
	v_mov_b32_dpp v148, v147 row_shl:4 row_mask:0xf bank_mask:0x5
	v_mov_b32_dpp v148, v147 row_shr:4 row_mask:0xf bank_mask:0xa
	v_mov_b32_dpp v149, v146 row_shl:4 row_mask:0xf bank_mask:0x5
	v_mov_b32_dpp v149, v146 row_shr:4 row_mask:0xf bank_mask:0xa
	s_waitcnt lgkmcnt(0)
	v_add_f32_e32 v147, v147, v148
	s_waitcnt lgkmcnt(0)
	v_add_f32_e32 v146, v146, v149
	v_mov_b32_dpp v148, v147 row_ror:8 row_mask:0xf bank_mask:0xf
	s_nop 1
	v_mov_b32_dpp v149, v146 row_ror:8 row_mask:0xf bank_mask:0xf
	s_waitcnt lgkmcnt(0)
	v_add_f32_e32 v147, v147, v148
	s_waitcnt lgkmcnt(0)
	v_add_f32_e32 v149, v146, v149
	ds_bpermute_b32 v148, v171, v147
	ds_bpermute_b32 v150, v171, v149
	s_waitcnt lgkmcnt(0)
	v_add_f32_e32 v146, v147, v148
	s_waitcnt lgkmcnt(0)
	v_add_f32_e32 v148, v149, v150
	ds_bpermute_b32 v147, v172, v146
	ds_bpermute_b32 v149, v172, v148
	s_and_saveexec_b64 s[8:9], s[52:53]
	s_cbranch_execnz .LBB0_667
	s_or_b64 exec, exec, s[8:9]
	s_and_b64 vcc, exec, s[72:73]
	s_cbranch_vccz .LBB0_670

.LBB0_670:
	v_lshl_or_b32 v70, v156, 4, v160
	v_readlane_b32 s8, v251, 13
	v_ashrrev_i32_e32 v71, 31, v70
	v_readlane_b32 s9, v251, 14
	v_mov_b32_dpp v152, v66 quad_perm:[2,3,0,1] row_mask:0xf bank_mask:0xf
	v_mov_b32_dpp v153, v67 quad_perm:[2,3,0,1] row_mask:0xf bank_mask:0xf
	s_waitcnt lgkmcnt(0)
	v_lshl_add_u64 v[148:149], v[70:71], 2, s[8:9]
	global_load_dwordx4 v[70:73], v[148:149], off offset:16
	s_nop 0
	global_load_dwordx4 v[148:151], v[148:149], off
	s_waitcnt vmcnt(0)
	v_mov_b32_e32 v155, v150
	v_mov_b32_e32 v150, v149
	v_mov_b32_e32 v154, v148
	s_waitcnt lgkmcnt(0)
	v_pk_mul_f32 v[148:149], v[150:151], v[152:153]
	v_mov_b32_e32 v151, v72
	v_cndmask_b32_e64 v149, v149, -v149, s[46:47]
	v_cndmask_b32_e64 v148, v148, -v148, s[46:47]
	v_pk_fma_f32 v[66:67], v[154:155], v[66:67], v[148:149]
	v_mov_b32_dpp v148, v68 quad_perm:[2,3,0,1] row_mask:0xf bank_mask:0xf
	v_mov_b32_dpp v149, v69 quad_perm:[2,3,0,1] row_mask:0xf bank_mask:0xf
	v_mov_b32_e32 v72, v71
	v_mov_b32_e32 v150, v70
	s_waitcnt lgkmcnt(0)
	v_pk_mul_f32 v[70:71], v[72:73], v[148:149]
	s_nop 0
	v_cndmask_b32_e64 v71, v71, -v71, s[46:47]
	v_cndmask_b32_e64 v70, v70, -v70, s[46:47]
	v_pk_fma_f32 v[68:69], v[150:151], v[68:69], v[70:71]
	s_and_saveexec_b64 s[8:9], s[56:57]
	s_cbranch_execz .LBB0_674

.LBB0_674:
	s_or_b64 exec, exec, s[8:9]
	s_waitcnt lgkmcnt(0)
	v_add_f32_e32 v66, v146, v147
	v_fmamk_f32 v66, v66, 0x3baaaaab, v219
	v_mul_f32_e32 v67, 0x4b800000, v66
	v_cmp_gt_f32_e32 vcc, s33, v66
	s_nop 1
	v_cndmask_b32_e32 v66, v66, v67, vcc
	v_rsq_f32_e32 v68, v66
	v_lshlrev_b32_e32 v66, 16, v144
	v_and_b32_e32 v67, 0xffff0000, v144
	v_mul_f32_e32 v69, 0x45800000, v68
	v_cndmask_b32_e32 v68, v68, v69, vcc
	v_pk_mul_f32 v[70:71], v[68:69], v[66:67] op_sel_hi:[0,1]
	v_lshlrev_b32_e32 v66, 16, v145
	v_and_b32_e32 v67, 0xffff0000, v145
	v_pk_mul_f32 v[72:73], v[68:69], v[66:67] op_sel_hi:[0,1]
	s_and_b64 vcc, exec, s[72:73]
	v_mov_b32_e32 v144, v70
	v_mov_b32_e32 v145, v71
	v_mov_b32_e32 v146, v72
	v_mov_b32_e32 v147, v73
	s_cbranch_vccnz .LBB0_676
	v_lshl_or_b32 v66, v156, 4, v160
	v_readlane_b32 s0, v251, 13
	v_ashrrev_i32_e32 v67, 31, v66
	v_readlane_b32 s1, v251, 14
	v_mov_b32_dpp v144, v70 quad_perm:[2,3,0,1] row_mask:0xf bank_mask:0xf
	v_mov_b32_dpp v145, v71 quad_perm:[2,3,0,1] row_mask:0xf bank_mask:0xf
	v_lshl_add_u64 v[66:67], v[66:67], 2, s[0:1]
	s_waitcnt lgkmcnt(0)
	global_load_dwordx4 v[146:149], v[66:67], off offset:16
	global_load_dwordx4 v[150:153], v[66:67], off
	s_waitcnt vmcnt(0)
	v_mov_b32_e32 v67, v152
	v_mov_b32_e32 v152, v151
	s_waitcnt lgkmcnt(0)
	v_pk_mul_f32 v[144:145], v[152:153], v[144:145]
	v_mov_b32_e32 v66, v150
	v_cndmask_b32_e64 v145, v145, -v145, s[46:47]
	v_cndmask_b32_e64 v144, v144, -v144, s[46:47]
	v_pk_fma_f32 v[144:145], v[70:71], v[66:67], v[144:145]
	v_mov_b32_dpp v66, v72 quad_perm:[2,3,0,1] row_mask:0xf bank_mask:0xf
	v_mov_b32_dpp v67, v73 quad_perm:[2,3,0,1] row_mask:0xf bank_mask:0xf
	v_mov_b32_e32 v151, v148
	v_mov_b32_e32 v148, v147
	v_mov_b32_e32 v150, v146
	s_waitcnt lgkmcnt(0)
	v_pk_mul_f32 v[66:67], v[148:149], v[66:67]
	s_nop 0
	v_cndmask_b32_e64 v67, v67, -v67, s[46:47]
	v_cndmask_b32_e64 v66, v66, -v66, s[46:47]
	v_pk_fma_f32 v[146:147], v[72:73], v[150:151], v[66:67]

.LBB0_678:
	s_or_b64 exec, exec, s[0:1]
	v_mov_b32_e32 v69, v68
	v_lshlrev_b32_e32 v70, 16, v142
	v_and_b32_e32 v71, 0xffff0000, v142
	v_lshlrev_b32_e32 v72, 16, v143
	v_and_b32_e32 v73, 0xffff0000, v143
	v_pk_mul_f32 v[70:71], v[68:69], v[70:71]
	v_pk_mul_f32 v[68:69], v[68:69], v[72:73]
	s_and_b64 vcc, exec, s[72:73]
	v_mov_b32_e32 v72, v70
	v_mov_b32_e32 v73, v71
	v_mov_b32_e32 v142, v68
	v_mov_b32_e32 v143, v69
	s_cbranch_vccnz .LBB0_680
	v_lshl_or_b32 v72, v156, 4, v160
	v_readlane_b32 s0, v251, 13
	v_ashrrev_i32_e32 v73, 31, v72
	v_readlane_b32 s1, v251, 14
	v_mov_b32_dpp v150, v70 quad_perm:[2,3,0,1] row_mask:0xf bank_mask:0xf
	v_mov_b32_dpp v151, v71 quad_perm:[2,3,0,1] row_mask:0xf bank_mask:0xf
	v_lshl_add_u64 v[72:73], v[72:73], 2, s[0:1]
	global_load_dwordx4 v[142:145], v[72:73], off offset:16
	s_waitcnt lgkmcnt(0)
	global_load_dwordx4 v[146:149], v[72:73], off
	s_waitcnt vmcnt(0)
	v_mov_b32_e32 v73, v148
	v_mov_b32_e32 v148, v147
	v_mov_b32_e32 v72, v146
	s_waitcnt lgkmcnt(0)
	v_pk_mul_f32 v[146:147], v[148:149], v[150:151]
	v_mov_b32_e32 v149, v144
	v_cndmask_b32_e64 v147, v147, -v147, s[46:47]
	v_cndmask_b32_e64 v146, v146, -v146, s[46:47]
	v_pk_fma_f32 v[72:73], v[70:71], v[72:73], v[146:147]
	v_mov_b32_dpp v146, v68 quad_perm:[2,3,0,1] row_mask:0xf bank_mask:0xf
	v_mov_b32_dpp v147, v69 quad_perm:[2,3,0,1] row_mask:0xf bank_mask:0xf
	v_mov_b32_e32 v144, v143
	v_mov_b32_e32 v148, v142
	s_waitcnt lgkmcnt(0)
	v_pk_mul_f32 v[142:143], v[144:145], v[146:147]
	s_nop 0
	v_cndmask_b32_e64 v143, v143, -v143, s[46:47]
	v_cndmask_b32_e64 v142, v142, -v142, s[46:47]
	v_pk_fma_f32 v[142:143], v[68:69], v[148:149], v[142:143]
